# final (no-setprio + memqk + loopedge + serial chain + norm-loop gain-load hoist) plus LDS-DMA via SGPR base + 32-bit VGPR offset (drops 12 v_lshl_add_u64 per tile)
# speedup vs baseline: 1.0106x; 1.0106x over previous
.LBB0_668:
	v_fmamk_f32 v2, v160, 0x3e0293ee, v14
	v_exp_f32_e32 v2, v2
	v_fmamk_f32 v3, v161, 0x3e0293ee, v14
	v_exp_f32_e32 v3, v3
	v_fmamk_f32 v4, v162, 0x3e0293ee, v14
	v_exp_f32_e32 v4, v4
	v_fmamk_f32 v5, v163, 0x3e0293ee, v14
	v_exp_f32_e32 v5, v5
	v_fmamk_f32 v7, v164, 0x3e0293ee, v14
	v_add_f32_e32 v6, 0, v2
	v_exp_f32_e32 v7, v7
	v_fmamk_f32 v8, v165, 0x3e0293ee, v14
	v_add_f32_e32 v6, v3, v6
	v_exp_f32_e32 v8, v8
	v_fmamk_f32 v9, v166, 0x3e0293ee, v14
	v_add_f32_e32 v6, v4, v6
	v_exp_f32_e32 v9, v9
	v_fmamk_f32 v10, v167, 0x3e0293ee, v14
	v_add_f32_e32 v6, v5, v6
	v_exp_f32_e32 v10, v10
	v_add_f32_e32 v6, v7, v6
	v_cvt_pk_bf16_f32 v2, v2, v3
	v_cvt_pk_bf16_f32 v3, v4, v5
	v_cvt_pk_bf16_f32 v4, v7, v8
	v_cvt_pk_bf16_f32 v5, v9, v10
	s_waitcnt lgkmcnt(0)
	v_add_f32_e32 v6, v8, v6
	s_add_i32 s45, s45, 1
	v_add_f32_e32 v6, v9, v6
	v_permlane32_swap_b32_e32 v2, v4
	v_add_u32_e32 v15, s4, v237
	v_add_f32_e32 v248, v10, v6
	v_permlane32_swap_b32_e32 v3, v5
	ds_read_b64_tr_b16 v[6:7], v15 offset:0
	ds_read_b64_tr_b16 v[8:9], v15 offset:0x800
	ds_read_b64_tr_b16 v[10:11], v15 offset:0x200
	ds_read_b64_tr_b16 v[12:13], v15 offset:0xa00
	ds_read_b64_tr_b16 v[160:161], v15 offset:0x400
	ds_read_b64_tr_b16 v[162:163], v15 offset:0xc00
	ds_read_b64_tr_b16 v[164:165], v15 offset:0x600
	ds_read_b64_tr_b16 v[166:167], v15 offset:0xe00
	v_add_u32_e32 v249, 0x4000, v15
	ds_read_b64_tr_b16 v[208:209], v249 offset:0
	ds_read_b64_tr_b16 v[210:211], v249 offset:0x800
	ds_read_b64_tr_b16 v[212:213], v249 offset:0x200
	ds_read_b64_tr_b16 v[214:215], v249 offset:0xa00
	ds_read_b64_tr_b16 v[240:241], v249 offset:0x400
	ds_read_b64_tr_b16 v[242:243], v249 offset:0xc00
	ds_read_b64_tr_b16 v[244:245], v249 offset:0x600
	ds_read_b64_tr_b16 v[246:247], v249 offset:0xe00
	s_waitcnt lgkmcnt(8)
	s_nop 0
	v_mfma_f32_32x32x16_bf16 v[128:143], v[2:5], v[6:9], v[128:143]
	v_fmamk_f32 v6, v168, 0x3e0293ee, v14
	v_exp_f32_e32 v168, v6
	v_fmamk_f32 v6, v169, 0x3e0293ee, v14
	v_exp_f32_e32 v169, v6
	v_fmamk_f32 v6, v170, 0x3e0293ee, v14
	v_exp_f32_e32 v170, v6
	v_fmamk_f32 v6, v171, 0x3e0293ee, v14
	v_mfma_f32_32x32x16_bf16 v[112:127], v[2:5], v[10:13], v[112:127]
	v_exp_f32_e32 v171, v6
	v_add_f32_e32 v6, v168, v248
	v_add_f32_e32 v6, v169, v6
	v_add_f32_e32 v6, v170, v6
	v_add_f32_e32 v248, v171, v6
	v_mfma_f32_32x32x16_bf16 v[96:111], v[2:5], v[160:163], v[96:111]
	v_mfma_f32_32x32x16_bf16 v[80:95], v[2:5], v[164:167], v[80:95]
	ds_read_b64_tr_b16 v[6:7], v15 offset:0x1000
	ds_read_b64_tr_b16 v[8:9], v15 offset:0x1800
	ds_read_b64_tr_b16 v[10:11], v15 offset:0x1200
	ds_read_b64_tr_b16 v[12:13], v15 offset:0x1a00
	ds_read_b64_tr_b16 v[160:161], v15 offset:0x1400
	ds_read_b64_tr_b16 v[162:163], v15 offset:0x1c00
	ds_read_b64_tr_b16 v[164:165], v15 offset:0x1600
	ds_read_b64_tr_b16 v[166:167], v15 offset:0x1e00
	s_waitcnt lgkmcnt(8)
	v_mfma_f32_32x32x16_bf16 v[64:79], v[2:5], v[208:211], v[64:79]
	v_fmamk_f32 v172, v172, 0x3e0293ee, v14
	v_exp_f32_e32 v172, v172
	v_fmamk_f32 v173, v173, 0x3e0293ee, v14
	v_exp_f32_e32 v173, v173
	v_fmamk_f32 v174, v174, 0x3e0293ee, v14
	v_exp_f32_e32 v174, v174
	v_fmamk_f32 v175, v175, 0x3e0293ee, v14
	v_mfma_f32_32x32x16_bf16 v[48:63], v[2:5], v[212:215], v[48:63]
	v_exp_f32_e32 v175, v175
	v_add_f32_e32 v208, v172, v248
	v_add_f32_e32 v208, v173, v208
	v_add_f32_e32 v208, v174, v208
	v_cvt_pk_bf16_f32 v168, v168, v169
	v_cvt_pk_bf16_f32 v169, v170, v171
	v_cvt_pk_bf16_f32 v170, v172, v173
	v_mfma_f32_32x32x16_bf16 v[32:47], v[2:5], v[240:243], v[32:47]
	v_cvt_pk_bf16_f32 v171, v174, v175
	v_add_f32_e32 v248, v175, v208
	v_permlane32_swap_b32_e32 v168, v170
	v_permlane32_swap_b32_e32 v169, v171
	v_mfma_f32_32x32x16_bf16 v[16:31], v[2:5], v[244:247], v[16:31]
	ds_read_b64_tr_b16 v[2:3], v249 offset:0x1000
	ds_read_b64_tr_b16 v[4:5], v249 offset:0x1800
	ds_read_b64_tr_b16 v[172:173], v249 offset:0x1200
	ds_read_b64_tr_b16 v[174:175], v249 offset:0x1a00
	ds_read_b64_tr_b16 v[208:209], v249 offset:0x1400
	ds_read_b64_tr_b16 v[210:211], v249 offset:0x1c00
	ds_read_b64_tr_b16 v[212:213], v249 offset:0x1600
	ds_read_b64_tr_b16 v[214:215], v249 offset:0x1e00
	s_waitcnt lgkmcnt(8)
	s_nop 0
	v_mfma_f32_32x32x16_bf16 v[128:143], v[168:171], v[6:9], v[128:143]
	v_fmamk_f32 v6, v144, 0x3e0293ee, v14
	v_exp_f32_e32 v240, v6
	v_fmamk_f32 v6, v145, 0x3e0293ee, v14
	v_exp_f32_e32 v241, v6
	v_fmamk_f32 v6, v146, 0x3e0293ee, v14
	v_exp_f32_e32 v242, v6
	v_fmamk_f32 v6, v147, 0x3e0293ee, v14
	v_mfma_f32_32x32x16_bf16 v[112:127], v[168:171], v[10:13], v[112:127]
	v_exp_f32_e32 v243, v6
	v_add_f32_e32 v6, v240, v248
	v_add_f32_e32 v6, v241, v6
	v_add_f32_e32 v6, v242, v6
	v_add_f32_e32 v244, v243, v6
	v_mfma_f32_32x32x16_bf16 v[96:111], v[168:171], v[160:163], v[96:111]
	v_mfma_f32_32x32x16_bf16 v[80:95], v[168:171], v[164:167], v[80:95]
	ds_read_b64_tr_b16 v[6:7], v15 offset:0x2000
	ds_read_b64_tr_b16 v[8:9], v15 offset:0x2800
	ds_read_b64_tr_b16 v[10:11], v15 offset:0x2200
	ds_read_b64_tr_b16 v[12:13], v15 offset:0x2a00
	ds_read_b64_tr_b16 v[144:145], v15 offset:0x2400
	ds_read_b64_tr_b16 v[146:147], v15 offset:0x2c00
	ds_read_b64_tr_b16 v[160:161], v15 offset:0x2600
	ds_read_b64_tr_b16 v[162:163], v15 offset:0x2e00
	s_waitcnt lgkmcnt(8)
	v_mfma_f32_32x32x16_bf16 v[64:79], v[168:171], v[2:5], v[64:79]
	v_fmamk_f32 v2, v148, 0x3e0293ee, v14
	v_exp_f32_e32 v4, v2
	v_fmamk_f32 v2, v149, 0x3e0293ee, v14
	v_exp_f32_e32 v5, v2
	v_fmamk_f32 v2, v150, 0x3e0293ee, v14
	v_exp_f32_e32 v148, v2
	v_fmamk_f32 v2, v151, 0x3e0293ee, v14
	v_mfma_f32_32x32x16_bf16 v[48:63], v[168:171], v[172:175], v[48:63]
	v_exp_f32_e32 v149, v2
	v_add_f32_e32 v2, v4, v244
	v_add_f32_e32 v2, v5, v2
	v_add_f32_e32 v2, v148, v2
	v_add_f32_e32 v244, v149, v2
	v_cvt_pk_bf16_f32 v2, v240, v241
	v_cvt_pk_bf16_f32 v3, v242, v243
	v_mfma_f32_32x32x16_bf16 v[32:47], v[168:171], v[208:211], v[32:47]
	v_cvt_pk_bf16_f32 v4, v4, v5
	v_cvt_pk_bf16_f32 v5, v148, v149
	s_nop 0
	v_permlane32_swap_b32_e32 v2, v4
	v_permlane32_swap_b32_e32 v3, v5
	v_mfma_f32_32x32x16_bf16 v[16:31], v[168:171], v[212:215], v[16:31]
	ds_read_b64_tr_b16 v[148:149], v249 offset:0x2000
	ds_read_b64_tr_b16 v[150:151], v249 offset:0x2800
	ds_read_b64_tr_b16 v[164:165], v249 offset:0x2200
	ds_read_b64_tr_b16 v[166:167], v249 offset:0x2a00
	ds_read_b64_tr_b16 v[168:169], v249 offset:0x2400
	ds_read_b64_tr_b16 v[170:171], v249 offset:0x2c00
	ds_read_b64_tr_b16 v[172:173], v249 offset:0x2600
	ds_read_b64_tr_b16 v[174:175], v249 offset:0x2e00
	s_waitcnt lgkmcnt(8)
	s_nop 0
	v_mfma_f32_32x32x16_bf16 v[128:143], v[2:5], v[6:9], v[128:143]
	v_fmamk_f32 v6, v152, 0x3e0293ee, v14
	v_exp_f32_e32 v208, v6
	v_fmamk_f32 v6, v153, 0x3e0293ee, v14
	v_exp_f32_e32 v209, v6
	v_fmamk_f32 v6, v154, 0x3e0293ee, v14
	v_exp_f32_e32 v210, v6
	v_fmamk_f32 v6, v155, 0x3e0293ee, v14
	v_mfma_f32_32x32x16_bf16 v[112:127], v[2:5], v[10:13], v[112:127]
	v_exp_f32_e32 v211, v6
	v_add_f32_e32 v6, v208, v244
	v_add_f32_e32 v6, v209, v6
	v_add_f32_e32 v6, v210, v6
	v_add_f32_e32 v212, v211, v6
	v_mfma_f32_32x32x16_bf16 v[96:111], v[2:5], v[144:147], v[96:111]
	v_mfma_f32_32x32x16_bf16 v[80:95], v[2:5], v[160:163], v[80:95]
	ds_read_b64_tr_b16 v[6:7], v15 offset:0x3000
	ds_read_b64_tr_b16 v[8:9], v15 offset:0x3800
	ds_read_b64_tr_b16 v[10:11], v15 offset:0x3200
	ds_read_b64_tr_b16 v[12:13], v15 offset:0x3a00
	ds_read_b64_tr_b16 v[144:145], v15 offset:0x3400
	ds_read_b64_tr_b16 v[146:147], v15 offset:0x3c00
	ds_read_b64_tr_b16 v[152:153], v15 offset:0x3600
	ds_read_b64_tr_b16 v[154:155], v15 offset:0x3e00
	s_waitcnt lgkmcnt(8)
	v_fmamk_f32 v15, v156, 0x3e0293ee, v14
	v_mfma_f32_32x32x16_bf16 v[64:79], v[2:5], v[148:151], v[64:79]
	v_exp_f32_e32 v15, v15
	v_fmamk_f32 v148, v157, 0x3e0293ee, v14
	v_exp_f32_e32 v150, v148
	v_fmamk_f32 v148, v158, 0x3e0293ee, v14
	v_exp_f32_e32 v151, v148
	v_fmac_f32_e32 v14, 0x3e0293ee, v159
	v_exp_f32_e32 v14, v14
	v_mfma_f32_32x32x16_bf16 v[48:63], v[2:5], v[164:167], v[48:63]
	v_add_f32_e32 v148, v15, v212
	v_add_f32_e32 v148, v150, v148
	v_add_f32_e32 v148, v151, v148
	v_add_f32_e32 v212, v14, v148
	v_cvt_pk_bf16_f32 v148, v208, v209
	v_cvt_pk_bf16_f32 v149, v210, v211
	v_cvt_pk_bf16_f32 v150, v15, v150
	v_mfma_f32_32x32x16_bf16 v[32:47], v[2:5], v[168:171], v[32:47]
	v_cvt_pk_bf16_f32 v151, v151, v14
	v_permlane32_swap_b32_e32 v148, v150
	v_permlane32_swap_b32_e32 v149, v151
	v_mfma_f32_32x32x16_bf16 v[16:31], v[2:5], v[172:175], v[16:31]
	ds_read_b64_tr_b16 v[2:3], v249 offset:0x3000
	ds_read_b64_tr_b16 v[4:5], v249 offset:0x3800
	ds_read_b64_tr_b16 v[156:157], v249 offset:0x3200
	ds_read_b64_tr_b16 v[158:159], v249 offset:0x3a00
	ds_read_b64_tr_b16 v[160:161], v249 offset:0x3400
	ds_read_b64_tr_b16 v[162:163], v249 offset:0x3c00
	ds_read_b64_tr_b16 v[164:165], v249 offset:0x3600
	ds_read_b64_tr_b16 v[166:167], v249 offset:0x3e00
	s_waitcnt lgkmcnt(8)
	s_nop 0
	v_mfma_f32_32x32x16_bf16 v[128:143], v[148:151], v[6:9], v[128:143]
	v_mfma_f32_32x32x16_bf16 v[112:127], v[148:151], v[10:13], v[112:127]
	v_mfma_f32_32x32x16_bf16 v[96:111], v[148:151], v[144:147], v[96:111]
	v_mfma_f32_32x32x16_bf16 v[80:95], v[148:151], v[152:155], v[80:95]
	s_waitcnt lgkmcnt(0)
	v_mfma_f32_32x32x16_bf16 v[64:79], v[148:151], v[2:5], v[64:79]
	v_mov_b32_e32 v2, v212
	s_nop 1
	v_permlane32_swap_b32_e32 v212, v2
	s_waitcnt vmcnt(0)
	v_add_f32_e32 v2, v212, v2
	v_fmac_f32_e32 v2, v239, v0
	v_mfma_f32_32x32x16_bf16 v[48:63], v[148:151], v[156:159], v[48:63]
	v_mov_b32_e32 v239, v2
	s_and_b32 s4, s45, 1
	s_cmpk_eq_i32 s45, 0xff
	s_cselect_b64 vcc, -1, 0
	s_cmpk_eq_i32 s45, 0x100
	s_waitcnt vmcnt(0) lgkmcnt(0)
	s_barrier
	v_mfma_f32_32x32x16_bf16 v[32:47], v[148:151], v[160:163], v[32:47]
	v_mfma_f32_32x32x16_bf16 v[16:31], v[148:151], v[164:167], v[16:31]
	s_cbranch_scc1 .LBB0_671
	s_cbranch_vccz .LBB0_662
	s_branch .LBB0_663

.LBB0_682:
	v_fmamk_f32 v146, v146, 0x3e0293ee, v248
	v_exp_f32_e32 v146, v146
	v_fmamk_f32 v147, v147, 0x3e0293ee, v248
	v_exp_f32_e32 v147, v147
	v_fmamk_f32 v148, v148, 0x3e0293ee, v248
	v_exp_f32_e32 v148, v148
	v_fmamk_f32 v149, v149, 0x3e0293ee, v248
	v_exp_f32_e32 v149, v149
	v_fmamk_f32 v150, v150, 0x3e0293ee, v248
	v_add_f32_e32 v194, 0, v146
	v_exp_f32_e32 v150, v150
	v_fmamk_f32 v151, v151, 0x3e0293ee, v248
	v_add_f32_e32 v194, v147, v194
	v_exp_f32_e32 v151, v151
	v_fmamk_f32 v152, v152, 0x3e0293ee, v248
	v_add_f32_e32 v194, v148, v194
	v_exp_f32_e32 v152, v152
	v_fmamk_f32 v153, v153, 0x3e0293ee, v248
	v_add_f32_e32 v194, v149, v194
	v_exp_f32_e32 v153, v153
	v_add_f32_e32 v194, v150, v194
	v_cvt_pk_bf16_f32 v146, v146, v147
	v_cvt_pk_bf16_f32 v147, v148, v149
	v_cvt_pk_bf16_f32 v148, v150, v151
	v_cvt_pk_bf16_f32 v149, v152, v153
	s_waitcnt lgkmcnt(0)
	v_add_f32_e32 v194, v151, v194
	s_add_i32 s34, s34, 1
	v_add_f32_e32 v194, v152, v194
	v_add_u32_e32 v249, s4, v237
	v_add_f32_e32 v250, v153, v194
	v_permlane32_swap_b32_e32 v146, v148
	v_permlane32_swap_b32_e32 v147, v149
	ds_read_b64_tr_b16 v[150:151], v249 offset:0
	ds_read_b64_tr_b16 v[152:153], v249 offset:0x800
	ds_read_b64_tr_b16 v[194:195], v249 offset:0x200
	ds_read_b64_tr_b16 v[196:197], v249 offset:0xa00
	ds_read_b64_tr_b16 v[198:199], v249 offset:0x400
	ds_read_b64_tr_b16 v[200:201], v249 offset:0xc00
	ds_read_b64_tr_b16 v[202:203], v249 offset:0x600
	ds_read_b64_tr_b16 v[204:205], v249 offset:0xe00
	v_add_u32_e32 v251, 0x4000, v249
	ds_read_b64_tr_b16 v[206:207], v251 offset:0
	ds_read_b64_tr_b16 v[208:209], v251 offset:0x800
	ds_read_b64_tr_b16 v[212:213], v251 offset:0x200
	ds_read_b64_tr_b16 v[214:215], v251 offset:0xa00
	ds_read_b64_tr_b16 v[240:241], v251 offset:0x400
	ds_read_b64_tr_b16 v[242:243], v251 offset:0xc00
	ds_read_b64_tr_b16 v[244:245], v251 offset:0x600
	ds_read_b64_tr_b16 v[246:247], v251 offset:0xe00
	s_waitcnt lgkmcnt(8)
	s_nop 0
	v_mfma_f32_32x32x16_bf16 v[2:17], v[146:149], v[150:153], v[2:17]
	v_fmamk_f32 v150, v154, 0x3e0293ee, v248
	v_exp_f32_e32 v252, v150
	v_fmamk_f32 v150, v155, 0x3e0293ee, v248
	v_exp_f32_e32 v231, v150
	v_fmamk_f32 v150, v156, 0x3e0293ee, v248
	v_exp_f32_e32 v232, v150
	v_fmamk_f32 v150, v157, 0x3e0293ee, v248
	v_mfma_f32_32x32x16_bf16 v[18:33], v[146:149], v[194:197], v[18:33]
	v_exp_f32_e32 v216, v150
	v_add_f32_e32 v150, v252, v250
	v_add_f32_e32 v150, v231, v150
	v_add_f32_e32 v150, v232, v150
	v_add_f32_e32 v217, v216, v150
	v_mfma_f32_32x32x16_bf16 v[34:49], v[146:149], v[198:201], v[34:49]
	v_mfma_f32_32x32x16_bf16 v[50:65], v[146:149], v[202:205], v[50:65]
	ds_read_b64_tr_b16 v[150:151], v249 offset:0x1000
	ds_read_b64_tr_b16 v[152:153], v249 offset:0x1800
	ds_read_b64_tr_b16 v[154:155], v249 offset:0x1200
	ds_read_b64_tr_b16 v[156:157], v249 offset:0x1a00
	ds_read_b64_tr_b16 v[194:195], v249 offset:0x1400
	ds_read_b64_tr_b16 v[196:197], v249 offset:0x1c00
	ds_read_b64_tr_b16 v[198:199], v249 offset:0x1600
	ds_read_b64_tr_b16 v[200:201], v249 offset:0x1e00
	s_waitcnt lgkmcnt(8)
	v_fmamk_f32 v158, v158, 0x3e0293ee, v248
	v_mfma_f32_32x32x16_bf16 v[66:81], v[146:149], v[206:209], v[66:81]
	v_exp_f32_e32 v202, v158
	v_fmamk_f32 v158, v159, 0x3e0293ee, v248
	v_exp_f32_e32 v203, v158
	v_fmamk_f32 v158, v160, 0x3e0293ee, v248
	v_exp_f32_e32 v204, v158
	v_fmamk_f32 v158, v161, 0x3e0293ee, v248
	v_exp_f32_e32 v161, v158
	v_mfma_f32_32x32x16_bf16 v[82:97], v[146:149], v[212:215], v[82:97]
	v_add_f32_e32 v158, v202, v217
	v_add_f32_e32 v158, v203, v158
	v_add_f32_e32 v158, v204, v158
	v_add_f32_e32 v217, v161, v158
	v_cvt_pk_bf16_f32 v158, v252, v231
	v_cvt_pk_bf16_f32 v159, v232, v216
	v_cvt_pk_bf16_f32 v160, v202, v203
	v_mfma_f32_32x32x16_bf16 v[98:113], v[146:149], v[240:243], v[98:113]
	v_cvt_pk_bf16_f32 v161, v204, v161
	v_permlane32_swap_b32_e32 v158, v160
	v_permlane32_swap_b32_e32 v159, v161
	v_mfma_f32_32x32x16_bf16 v[114:129], v[146:149], v[244:247], v[114:129]
	ds_read_b64_tr_b16 v[146:147], v251 offset:0x1000
	ds_read_b64_tr_b16 v[148:149], v251 offset:0x1800
	ds_read_b64_tr_b16 v[202:203], v251 offset:0x1200
	ds_read_b64_tr_b16 v[204:205], v251 offset:0x1a00
	ds_read_b64_tr_b16 v[206:207], v251 offset:0x1400
	ds_read_b64_tr_b16 v[208:209], v251 offset:0x1c00
	ds_read_b64_tr_b16 v[212:213], v251 offset:0x1600
	ds_read_b64_tr_b16 v[214:215], v251 offset:0x1e00
	s_waitcnt lgkmcnt(8)
	s_nop 0
	v_mfma_f32_32x32x16_bf16 v[2:17], v[158:161], v[150:153], v[2:17]
	v_fmamk_f32 v130, v130, 0x3e0293ee, v248
	v_exp_f32_e32 v216, v130
	v_fmamk_f32 v130, v131, 0x3e0293ee, v248
	v_exp_f32_e32 v231, v130
	v_fmamk_f32 v130, v132, 0x3e0293ee, v248
	v_exp_f32_e32 v232, v130
	v_fmamk_f32 v130, v133, 0x3e0293ee, v248
	v_mfma_f32_32x32x16_bf16 v[18:33], v[158:161], v[154:157], v[18:33]
	v_exp_f32_e32 v240, v130
	v_add_f32_e32 v130, v216, v217
	v_add_f32_e32 v130, v231, v130
	v_add_f32_e32 v130, v232, v130
	v_add_f32_e32 v217, v240, v130
	v_mfma_f32_32x32x16_bf16 v[34:49], v[158:161], v[194:197], v[34:49]
	v_mfma_f32_32x32x16_bf16 v[50:65], v[158:161], v[198:201], v[50:65]
	ds_read_b64_tr_b16 v[130:131], v249 offset:0x2000
	ds_read_b64_tr_b16 v[132:133], v249 offset:0x2800
	ds_read_b64_tr_b16 v[150:151], v249 offset:0x2200
	ds_read_b64_tr_b16 v[152:153], v249 offset:0x2a00
	ds_read_b64_tr_b16 v[154:155], v249 offset:0x2400
	ds_read_b64_tr_b16 v[156:157], v249 offset:0x2c00
	ds_read_b64_tr_b16 v[194:195], v249 offset:0x2600
	ds_read_b64_tr_b16 v[196:197], v249 offset:0x2e00
	s_waitcnt lgkmcnt(8)
	v_fmamk_f32 v134, v134, 0x3e0293ee, v248
	v_mfma_f32_32x32x16_bf16 v[66:81], v[158:161], v[146:149], v[66:81]
	v_exp_f32_e32 v146, v134
	v_fmamk_f32 v134, v135, 0x3e0293ee, v248
	v_exp_f32_e32 v147, v134
	v_fmamk_f32 v134, v136, 0x3e0293ee, v248
	v_exp_f32_e32 v148, v134
	v_fmamk_f32 v134, v137, 0x3e0293ee, v248
	v_exp_f32_e32 v137, v134
	v_mfma_f32_32x32x16_bf16 v[82:97], v[158:161], v[202:205], v[82:97]
	v_add_f32_e32 v134, v146, v217
	v_add_f32_e32 v134, v147, v134
	v_add_f32_e32 v134, v148, v134
	v_add_f32_e32 v217, v137, v134
	v_cvt_pk_bf16_f32 v134, v216, v231
	v_cvt_pk_bf16_f32 v135, v232, v240
	v_cvt_pk_bf16_f32 v136, v146, v147
	v_mfma_f32_32x32x16_bf16 v[98:113], v[158:161], v[206:209], v[98:113]
	v_cvt_pk_bf16_f32 v137, v148, v137
	v_permlane32_swap_b32_e32 v134, v136
	v_permlane32_swap_b32_e32 v135, v137
	v_mfma_f32_32x32x16_bf16 v[114:129], v[158:161], v[212:215], v[114:129]
	ds_read_b64_tr_b16 v[146:147], v251 offset:0x2000
	ds_read_b64_tr_b16 v[148:149], v251 offset:0x2800
	ds_read_b64_tr_b16 v[158:159], v251 offset:0x2200
	ds_read_b64_tr_b16 v[160:161], v251 offset:0x2a00
	ds_read_b64_tr_b16 v[198:199], v251 offset:0x2400
	ds_read_b64_tr_b16 v[200:201], v251 offset:0x2c00
	ds_read_b64_tr_b16 v[202:203], v251 offset:0x2600
	ds_read_b64_tr_b16 v[204:205], v251 offset:0x2e00
	s_waitcnt lgkmcnt(8)
	s_nop 0
	v_mfma_f32_32x32x16_bf16 v[2:17], v[134:137], v[130:133], v[2:17]
	v_fmamk_f32 v130, v138, 0x3e0293ee, v248
	v_exp_f32_e32 v206, v130
	v_fmamk_f32 v130, v139, 0x3e0293ee, v248
	v_exp_f32_e32 v207, v130
	v_fmamk_f32 v130, v140, 0x3e0293ee, v248
	v_exp_f32_e32 v208, v130
	v_fmamk_f32 v130, v141, 0x3e0293ee, v248
	v_mfma_f32_32x32x16_bf16 v[18:33], v[134:137], v[150:153], v[18:33]
	v_exp_f32_e32 v209, v130
	v_add_f32_e32 v130, v206, v217
	v_add_f32_e32 v130, v207, v130
	v_add_f32_e32 v130, v208, v130
	v_add_f32_e32 v212, v209, v130
	v_mfma_f32_32x32x16_bf16 v[34:49], v[134:137], v[154:157], v[34:49]
	v_mfma_f32_32x32x16_bf16 v[50:65], v[134:137], v[194:197], v[50:65]
	ds_read_b64_tr_b16 v[130:131], v249 offset:0x3000
	ds_read_b64_tr_b16 v[132:133], v249 offset:0x3800
	ds_read_b64_tr_b16 v[138:139], v249 offset:0x3200
	ds_read_b64_tr_b16 v[140:141], v249 offset:0x3a00
	ds_read_b64_tr_b16 v[150:151], v249 offset:0x3400
	ds_read_b64_tr_b16 v[152:153], v249 offset:0x3c00
	ds_read_b64_tr_b16 v[154:155], v249 offset:0x3600
	ds_read_b64_tr_b16 v[156:157], v249 offset:0x3e00
	s_waitcnt lgkmcnt(8)
	v_fmamk_f32 v142, v142, 0x3e0293ee, v248
	v_mfma_f32_32x32x16_bf16 v[66:81], v[134:137], v[146:149], v[66:81]
	v_exp_f32_e32 v146, v142
	v_fmamk_f32 v142, v143, 0x3e0293ee, v248
	v_exp_f32_e32 v147, v142
	v_fmamk_f32 v142, v144, 0x3e0293ee, v248
	v_exp_f32_e32 v148, v142
	v_fmac_f32_e32 v248, 0x3e0293ee, v145
	v_exp_f32_e32 v145, v248
	v_mfma_f32_32x32x16_bf16 v[82:97], v[134:137], v[158:161], v[82:97]
	v_add_f32_e32 v142, v146, v212
	v_add_f32_e32 v142, v147, v142
	v_add_f32_e32 v142, v148, v142
	v_add_f32_e32 v212, v145, v142
	v_cvt_pk_bf16_f32 v142, v206, v207
	v_cvt_pk_bf16_f32 v143, v208, v209
	v_cvt_pk_bf16_f32 v144, v146, v147
	v_mfma_f32_32x32x16_bf16 v[98:113], v[134:137], v[198:201], v[98:113]
	v_cvt_pk_bf16_f32 v145, v148, v145
	v_permlane32_swap_b32_e32 v142, v144
	v_permlane32_swap_b32_e32 v143, v145
	v_mfma_f32_32x32x16_bf16 v[114:129], v[134:137], v[202:205], v[114:129]
	ds_read_b64_tr_b16 v[134:135], v251 offset:0x3000
	ds_read_b64_tr_b16 v[136:137], v251 offset:0x3800
	ds_read_b64_tr_b16 v[146:147], v251 offset:0x3200
	ds_read_b64_tr_b16 v[148:149], v251 offset:0x3a00
	ds_read_b64_tr_b16 v[158:159], v251 offset:0x3400
	ds_read_b64_tr_b16 v[160:161], v251 offset:0x3c00
	ds_read_b64_tr_b16 v[194:195], v251 offset:0x3600
	ds_read_b64_tr_b16 v[196:197], v251 offset:0x3e00
	s_waitcnt lgkmcnt(8)
	s_nop 0
	v_mfma_f32_32x32x16_bf16 v[2:17], v[142:145], v[130:133], v[2:17]
	v_mfma_f32_32x32x16_bf16 v[18:33], v[142:145], v[138:141], v[18:33]
	v_mfma_f32_32x32x16_bf16 v[34:49], v[142:145], v[150:153], v[34:49]
	v_mfma_f32_32x32x16_bf16 v[50:65], v[142:145], v[154:157], v[50:65]
	s_waitcnt lgkmcnt(0)
	v_mfma_f32_32x32x16_bf16 v[66:81], v[142:145], v[134:137], v[66:81]
	v_mov_b32_e32 v130, v212
	s_nop 1
	v_permlane32_swap_b32_e32 v212, v130
	s_waitcnt vmcnt(0)
	v_add_f32_e32 v130, v212, v130
	v_fmac_f32_e32 v130, v239, v0
	v_mfma_f32_32x32x16_bf16 v[82:97], v[142:145], v[146:149], v[82:97]
	v_mov_b32_e32 v239, v130
	s_and_b32 s4, s34, 1
	s_cmpk_eq_i32 s34, 0xff
	s_cselect_b64 vcc, -1, 0
	s_cmpk_eq_i32 s34, 0x100
	s_waitcnt vmcnt(0) lgkmcnt(0)
	s_barrier
	v_mfma_f32_32x32x16_bf16 v[98:113], v[142:145], v[158:161], v[98:113]
	v_mfma_f32_32x32x16_bf16 v[114:129], v[142:145], v[194:197], v[114:129]
	s_cbranch_scc1 .LBB0_685
	s_cbranch_vccz .LBB0_676
	s_branch .LBB0_677
